# E41: the 16th of 32 arrivers per XCD at each grid barrier issues an early L2 writeback so the last arriver's writeback has less to flush
# speedup vs baseline: 1.0003x; 1.0003x over previous
.LBB0_166:
	s_or_b64 exec, exec, s[4:5]
	s_mov_b32 s100, 0
	v_readlane_b32 s98, v255, 37
	v_cvt_f32_u32_e32 v4, v0
	s_waitcnt vmcnt(0)
	v_readfirstlane_b32 s4, v3
	s_mov_b32 s20, 1
	v_rcp_iflag_f32_e32 v4, v4
	v_add_u32_e32 v1, s4, v1
	v_mul_f32_e32 v3, 0x4f7ffffe, v4
	v_cvt_u32_f32_e32 v3, v3
	v_sub_u32_e32 v4, 0, v0
	v_mul_lo_u32 v4, v4, v3
	v_mul_hi_u32 v4, v3, v4
	v_add_u32_e32 v3, v3, v4
	v_mul_hi_u32 v3, v1, v3
	v_mul_lo_u32 v4, v3, v0
	v_sub_u32_e32 v4, v1, v4
	v_add_u32_e32 v5, 1, v3
	v_cmp_ge_u32_e32 vcc, v4, v0
	v_add_u32_e32 v1, 1, v1
	s_nop 0
	v_cndmask_b32_e32 v3, v3, v5, vcc
	v_sub_u32_e32 v5, v4, v0
	v_cndmask_b32_e32 v4, v4, v5, vcc
	v_add_u32_e32 v5, 1, v3
	v_cmp_ge_u32_e32 vcc, v4, v0
	s_nop 1
	v_cndmask_b32_e32 v3, v3, v5, vcc
	v_add_u32_e32 v3, 1, v3
	v_mul_lo_u32 v0, v3, v0
	v_cmp_eq_u32_e32 vcc, 15, v4
	s_and_saveexec_b64 s[4:5], vcc
	s_cbranch_execz .Lhalfwb_skip_1
	buffer_wbl2 sc1
	s_waitcnt vmcnt(0)
.Lhalfwb_skip_1:
	s_or_b64 exec, exec, s[4:5]
	v_cmp_eq_u32_e32 vcc, v1, v0
	s_and_saveexec_b64 s[4:5], vcc
	s_cbranch_execz .LBB0_168
	v_readlane_b32 s6, v255, 37
	s_lshl_b32 s6, s6, 2
	v_readlane_b32 s8, v255, 35
	buffer_wbl2 sc1
	s_waitcnt lgkmcnt(0)
	s_waitcnt vmcnt(0)
	v_readlane_b32 s9, v255, 36
	s_add_u32 s6, s8, s6
	s_addc_u32 s7, s9, 0
	v_mov_b32_e32 v0, 0x3000
	global_store_dword v0, v3, s[6:7] offset:1024 sc1

.LBB0_2342:
	s_or_b64 exec, exec, s[2:3]
	s_mov_b32 s100, 0
	v_readlane_b32 s98, v255, 37
	v_cvt_f32_u32_e32 v4, v0
	s_waitcnt vmcnt(0)
	v_readfirstlane_b32 s2, v3
	s_mov_b32 s18, 1
	v_rcp_iflag_f32_e32 v4, v4
	v_add_u32_e32 v1, s2, v1
	v_mul_f32_e32 v3, 0x4f7ffffe, v4
	v_cvt_u32_f32_e32 v3, v3
	v_sub_u32_e32 v4, 0, v0
	v_mul_lo_u32 v4, v4, v3
	v_mul_hi_u32 v4, v3, v4
	v_add_u32_e32 v3, v3, v4
	v_mul_hi_u32 v3, v1, v3
	v_mul_lo_u32 v4, v3, v0
	v_sub_u32_e32 v4, v1, v4
	v_add_u32_e32 v5, 1, v3
	v_cmp_ge_u32_e32 vcc, v4, v0
	v_add_u32_e32 v1, 1, v1
	s_nop 0
	v_cndmask_b32_e32 v3, v3, v5, vcc
	v_sub_u32_e32 v5, v4, v0
	v_cndmask_b32_e32 v4, v4, v5, vcc
	v_add_u32_e32 v5, 1, v3
	v_cmp_ge_u32_e32 vcc, v4, v0
	s_nop 1
	v_cndmask_b32_e32 v3, v3, v5, vcc
	v_add_u32_e32 v3, 1, v3
	v_mul_lo_u32 v0, v3, v0
	v_cmp_eq_u32_e32 vcc, 15, v4
	s_and_saveexec_b64 s[2:3], vcc
	s_cbranch_execz .Lhalfwb_skip_6
	buffer_wbl2 sc1
	s_waitcnt vmcnt(0)
.Lhalfwb_skip_6:
	s_or_b64 exec, exec, s[2:3]
	v_cmp_eq_u32_e32 vcc, v1, v0
	s_and_saveexec_b64 s[2:3], vcc
	s_cbranch_execz .LBB0_2344
	v_readlane_b32 s4, v255, 37
	s_lshl_b32 s4, s4, 2
	v_readlane_b32 s6, v255, 35
	buffer_wbl2 sc1
	s_waitcnt lgkmcnt(0)
	s_waitcnt vmcnt(0)
	v_readlane_b32 s7, v255, 36
	s_add_u32 s4, s6, s4
	s_addc_u32 s5, s7, 0
	v_mov_b32_e32 v0, 0x3000
	global_store_dword v0, v3, s[4:5] offset:1024 sc1
